# code placement: the seven GEMM K-loop heads aligned to 64 bytes
# baseline (speedup 1.0000x reference)
; #define PG8_WAIT_V(n) asm volatile("s_waitcnt vmcnt(" #n ")" ::: "memory")
; #define PG8_WAIT_L(n) asm volatile("s_waitcnt lgkmcnt(" #n ")" ::: "memory")
; template <class Epi, class Sched, bool ALIGN_EPI>
; __device__ __forceinline__ void gemm_phase(LAS unsigned char* lds, const GemmDesc g, const Sched& S, const Epi& E) {
;     ...
;         const bool has_next = S.next(ui + 1, nxt);
;         const char* nA = has_next ? S.aptr(nxt) : cA; const char* nB = has_next ? S.bptr(nxt) : cB;
;         for (int t = 0; t < nt; t += 2) {
;             const bool last = (t == nt - 2);
;             const char* a1 = cA + (size_t)(t + 1) * kstep;
;             const char* a2 = last ? nA : cA + (size_t)(t + 2) * kstep; const char* b2 = last ? nB : cB + (size_t)(t + 2) * kstep;
;             const char* a3 = a2 + kstep; const char* b3 = b2 + kstep;
;             PG8_LDB(B0, 0, 0); PG8_LDB(B1, 0, 1); PG8_SCHED; PG8_LDA(At, 0, 0); PG8_STAGE(PG8_SA(1, 1), a1 + hstepA, voffA);
;             PG8_WAIT_V(8); PG8_WAIT_L(0); PG8_BAR; PG8_MMA(0, 0, At, B0); PG8_MMA(0, 1, At, B1); PG8_BAR; PG8_SCHED;
;             PG8_LDA(At, 0, 1); PG8_STAGE(PG8_SB(0, 0), b2, voffB); PG8_STAGE(PG8_SB(0, 1), b2 + hstepB, voffB); PG8_STAGE(PG8_SA(0, 0), a2, voffA);
;             PG8_WAIT_V(8); PG8_WAIT_L(0); PG8_BAR; PG8_MMA(1, 0, At, B0); PG8_MMA(1, 1, At, B1); PG8_BAR; PG8_SCHED;
;             PG8_LDB(B0, 1, 0); PG8_LDB(B1, 1, 1); PG8_SCHED; PG8_LDA(At, 1, 0); PG8_STAGE(PG8_SA(0, 1), a2 + hstepA, voffA);
;             PG8_WAIT_V(8); PG8_WAIT_L(0); PG8_BAR; PG8_MMA(0, 0, At, B0); PG8_MMA(0, 1, At, B1); PG8_BAR; PG8_SCHED;
;             PG8_LDA(At, 1, 1); PG8_STAGE(PG8_SB(1, 0), b3, voffB); PG8_STAGE(PG8_SB(1, 1), b3 + hstepB, voffB); PG8_STAGE(PG8_SA(1, 0), a3, voffA);
;             PG8_WAIT_V(8); PG8_WAIT_L(0); PG8_BAR; PG8_MMA(1, 0, At, B0); PG8_MMA(1, 1, At, B1); PG8_BAR; PG8_SCHED;
;         }
;         if constexpr (ALIGN_EPI) { if (wr == 0) PG8_BAR; }
;         E(acc, cur, wr, wc, fr, fq, lds + STAGE_BYTES);
;         if (!has_next) break;
; #pragma unroll
;         for (int a = 0; a < 2; ++a)
; #pragma unroll
;             for (int b = 0; b < 2; ++b)
; #pragma unroll
;                 for (int m = 0; m < 4; ++m)
; #pragma unroll
;                     for (int n = 0; n < 2; ++n) acc[a][b][m][n] = (f32x4){0.f, 0.f, 0.f, 0.f};
;         cur = nxt; cA = nA; cB = nB; ++ui;
.LBB0_327:
	s_ashr_i32 s23, s22, 31
	s_lshl_b64 s[26:27], s[22:23], 11
	s_add_u32 s38, s44, s26
	s_addc_u32 s39, s45, s27
	s_and_b64 s[26:27], s[0:1], exec
	s_cselect_b32 s17, s39, s5
	s_cselect_b32 s23, s38, s4
	s_ashr_i32 s25, s24, 31
	s_lshl_b64 s[26:27], s[24:25], 11
	s_add_u32 s42, s66, s26
	s_addc_u32 s43, s67, s27
	s_and_b64 s[26:27], s[0:1], exec
	s_cselect_b32 s25, s43, s29
	s_cselect_b32 s26, s42, s28
	s_add_u32 s4, s4, 0x40080
	s_addc_u32 s5, s5, 0
	s_add_u32 s27, s28, 0x100
	v_mov_b32_e32 v0, 0
	s_addc_u32 s62, s29, 0
	s_mov_b32 s63, -2
	v_mov_b32_e32 v1, v0
	v_mov_b32_e32 v2, v0
	v_mov_b32_e32 v3, v0
	v_mov_b32_e32 v4, v0
	v_mov_b32_e32 v5, v0
	v_mov_b32_e32 v6, v0
	v_mov_b32_e32 v7, v0
	v_mov_b32_e32 v16, v0
	v_mov_b32_e32 v17, v0
	v_mov_b32_e32 v18, v0
	v_mov_b32_e32 v19, v0
	v_mov_b32_e32 v20, v0
	v_mov_b32_e32 v21, v0
	v_mov_b32_e32 v22, v0
	v_mov_b32_e32 v23, v0
	v_mov_b32_e32 v32, v0
	v_mov_b32_e32 v33, v0
	v_mov_b32_e32 v34, v0
	v_mov_b32_e32 v35, v0
	v_mov_b32_e32 v36, v0
	v_mov_b32_e32 v37, v0
	v_mov_b32_e32 v38, v0
	v_mov_b32_e32 v39, v0
	v_mov_b32_e32 v48, v0
	v_mov_b32_e32 v49, v0
	v_mov_b32_e32 v50, v0
	v_mov_b32_e32 v51, v0
	v_mov_b32_e32 v52, v0
	v_mov_b32_e32 v53, v0
	v_mov_b32_e32 v54, v0
	v_mov_b32_e32 v55, v0
	v_mov_b32_e32 v8, v0
	v_mov_b32_e32 v9, v0
	v_mov_b32_e32 v10, v0
	v_mov_b32_e32 v11, v0
	v_mov_b32_e32 v12, v0
	v_mov_b32_e32 v13, v0
	v_mov_b32_e32 v14, v0
	v_mov_b32_e32 v15, v0
	v_mov_b32_e32 v24, v0
	v_mov_b32_e32 v25, v0
	v_mov_b32_e32 v26, v0
	v_mov_b32_e32 v27, v0
	v_mov_b32_e32 v28, v0
	v_mov_b32_e32 v29, v0
	v_mov_b32_e32 v30, v0
	v_mov_b32_e32 v31, v0
	v_mov_b32_e32 v40, v0
	v_mov_b32_e32 v41, v0
	v_mov_b32_e32 v42, v0
	v_mov_b32_e32 v43, v0
	v_mov_b32_e32 v44, v0
	v_mov_b32_e32 v45, v0
	v_mov_b32_e32 v46, v0
	v_mov_b32_e32 v47, v0
	v_mov_b32_e32 v56, v0
	v_mov_b32_e32 v57, v0
	v_mov_b32_e32 v58, v0
	v_mov_b32_e32 v59, v0
	v_mov_b32_e32 v60, v0
	v_mov_b32_e32 v61, v0
	v_mov_b32_e32 v62, v0
	v_mov_b32_e32 v63, v0
	v_mov_b32_e32 v64, v0
	v_mov_b32_e32 v65, v0
	v_mov_b32_e32 v66, v0
	v_mov_b32_e32 v67, v0
	v_mov_b32_e32 v68, v0
	v_mov_b32_e32 v69, v0
	v_mov_b32_e32 v70, v0
	v_mov_b32_e32 v71, v0
	v_mov_b32_e32 v80, v0
	v_mov_b32_e32 v81, v0
	v_mov_b32_e32 v82, v0
	v_mov_b32_e32 v83, v0
	v_mov_b32_e32 v84, v0
	v_mov_b32_e32 v85, v0
	v_mov_b32_e32 v86, v0
	v_mov_b32_e32 v87, v0
	v_mov_b32_e32 v96, v0
	v_mov_b32_e32 v97, v0
	v_mov_b32_e32 v98, v0
	v_mov_b32_e32 v99, v0
	v_mov_b32_e32 v100, v0
	v_mov_b32_e32 v101, v0
	v_mov_b32_e32 v102, v0
	v_mov_b32_e32 v103, v0
	v_mov_b32_e32 v112, v0
	v_mov_b32_e32 v113, v0
	v_mov_b32_e32 v114, v0
	v_mov_b32_e32 v115, v0
	v_mov_b32_e32 v116, v0
	v_mov_b32_e32 v117, v0
	v_mov_b32_e32 v118, v0
	v_mov_b32_e32 v119, v0
	v_mov_b32_e32 v72, v0
	v_mov_b32_e32 v73, v0
	v_mov_b32_e32 v74, v0
	v_mov_b32_e32 v75, v0
	v_mov_b32_e32 v76, v0
	v_mov_b32_e32 v77, v0
	v_mov_b32_e32 v78, v0
	v_mov_b32_e32 v79, v0
	v_mov_b32_e32 v88, v0
	v_mov_b32_e32 v89, v0
	v_mov_b32_e32 v90, v0
	v_mov_b32_e32 v91, v0
	v_mov_b32_e32 v92, v0
	v_mov_b32_e32 v93, v0
	v_mov_b32_e32 v94, v0
	v_mov_b32_e32 v95, v0
	v_mov_b32_e32 v104, v0
	v_mov_b32_e32 v105, v0
	v_mov_b32_e32 v106, v0
	v_mov_b32_e32 v107, v0
	v_mov_b32_e32 v108, v0
	v_mov_b32_e32 v109, v0
	v_mov_b32_e32 v110, v0
	v_mov_b32_e32 v111, v0
	v_mov_b32_e32 v120, v0
	v_mov_b32_e32 v121, v0
	v_mov_b32_e32 v122, v0
	v_mov_b32_e32 v123, v0
	v_mov_b32_e32 v124, v0
	v_mov_b32_e32 v125, v0
	v_mov_b32_e32 v126, v0
	v_mov_b32_e32 v127, v0
	.p2align 6

; #define PG8_WAIT_V(n) asm volatile("s_waitcnt vmcnt(" #n ")" ::: "memory")
; #define PG8_WAIT_L(n) asm volatile("s_waitcnt lgkmcnt(" #n ")" ::: "memory")
; template <class Epi, class Sched, bool ALIGN_EPI>
; __device__ __forceinline__ void gemm_phase(LAS unsigned char* lds, const GemmDesc g, const Sched& S, const Epi& E) {
;     ...
;         const bool has_next = S.next(ui + 1, nxt);
;         const char* nA = has_next ? S.aptr(nxt) : cA; const char* nB = has_next ? S.bptr(nxt) : cB;
;         for (int t = 0; t < nt; t += 2) {
;             const bool last = (t == nt - 2);
;             const char* a1 = cA + (size_t)(t + 1) * kstep;
;             const char* a2 = last ? nA : cA + (size_t)(t + 2) * kstep; const char* b2 = last ? nB : cB + (size_t)(t + 2) * kstep;
;             const char* a3 = a2 + kstep; const char* b3 = b2 + kstep;
;             PG8_LDB(B0, 0, 0); PG8_LDB(B1, 0, 1); PG8_SCHED; PG8_LDA(At, 0, 0); PG8_STAGE(PG8_SA(1, 1), a1 + hstepA, voffA);
;             PG8_WAIT_V(8); PG8_WAIT_L(0); PG8_BAR; PG8_MMA(0, 0, At, B0); PG8_MMA(0, 1, At, B1); PG8_BAR; PG8_SCHED;
;             PG8_LDA(At, 0, 1); PG8_STAGE(PG8_SB(0, 0), b2, voffB); PG8_STAGE(PG8_SB(0, 1), b2 + hstepB, voffB); PG8_STAGE(PG8_SA(0, 0), a2, voffA);
;             PG8_WAIT_V(8); PG8_WAIT_L(0); PG8_BAR; PG8_MMA(1, 0, At, B0); PG8_MMA(1, 1, At, B1); PG8_BAR; PG8_SCHED;
;             PG8_LDB(B0, 1, 0); PG8_LDB(B1, 1, 1); PG8_SCHED; PG8_LDA(At, 1, 0); PG8_STAGE(PG8_SA(0, 1), a2 + hstepA, voffA);
;             PG8_WAIT_V(8); PG8_WAIT_L(0); PG8_BAR; PG8_MMA(0, 0, At, B0); PG8_MMA(0, 1, At, B1); PG8_BAR; PG8_SCHED;
;             PG8_LDA(At, 1, 1); PG8_STAGE(PG8_SB(1, 0), b3, voffB); PG8_STAGE(PG8_SB(1, 1), b3 + hstepB, voffB); PG8_STAGE(PG8_SA(1, 0), a3, voffA);
;             PG8_WAIT_V(8); PG8_WAIT_L(0); PG8_BAR; PG8_MMA(1, 0, At, B0); PG8_MMA(1, 1, At, B1); PG8_BAR; PG8_SCHED;
;         }
;         if constexpr (ALIGN_EPI) { if (wr == 0) PG8_BAR; }
;         E(acc, cur, wr, wc, fr, fq, lds + STAGE_BYTES);
;         if (!has_next) break;
; #pragma unroll
;         for (int a = 0; a < 2; ++a)
; #pragma unroll
;             for (int b = 0; b < 2; ++b)
; #pragma unroll
;                 for (int m = 0; m < 4; ++m)
; #pragma unroll
;                     for (int n = 0; n < 2; ++n) acc[a][b][m][n] = (f32x4){0.f, 0.f, 0.f, 0.f};
;         cur = nxt; cA = nA; cB = nB; ++ui;
.LBB0_739:
	s_ashr_i32 s13, s12, 31
	s_lshl_b64 s[16:17], s[12:13], 10
	s_add_u32 s16, s46, s16
	s_addc_u32 s17, s47, s17
	s_and_b64 s[20:21], s[4:5], exec
	s_cselect_b32 s13, s17, s25
	s_cselect_b32 s19, s16, s24
	s_ashr_i32 s15, s14, 31
	s_lshl_b64 s[20:21], s[14:15], 10
	s_add_u32 s20, s3, s20
	s_addc_u32 s21, s30, s21
	s_and_b64 s[28:29], s[4:5], exec
	s_cselect_b32 s15, s21, s27
	s_cselect_b32 s42, s20, s26
	s_add_u32 s24, s24, 0x20080
	s_addc_u32 s25, s25, 0
	s_add_u32 s43, s26, 0x100
	v_mov_b32_e32 v0, 0
	s_addc_u32 s68, s27, 0
	s_mov_b32 s69, -2
	v_mov_b32_e32 v1, v0
	v_mov_b32_e32 v2, v0
	v_mov_b32_e32 v3, v0
	v_mov_b32_e32 v4, v0
	v_mov_b32_e32 v5, v0
	v_mov_b32_e32 v6, v0
	v_mov_b32_e32 v7, v0
	v_mov_b32_e32 v16, v0
	v_mov_b32_e32 v17, v0
	v_mov_b32_e32 v18, v0
	v_mov_b32_e32 v19, v0
	v_mov_b32_e32 v20, v0
	v_mov_b32_e32 v21, v0
	v_mov_b32_e32 v22, v0
	v_mov_b32_e32 v23, v0
	v_mov_b32_e32 v32, v0
	v_mov_b32_e32 v33, v0
	v_mov_b32_e32 v34, v0
	v_mov_b32_e32 v35, v0
	v_mov_b32_e32 v36, v0
	v_mov_b32_e32 v37, v0
	v_mov_b32_e32 v38, v0
	v_mov_b32_e32 v39, v0
	v_mov_b32_e32 v48, v0
	v_mov_b32_e32 v49, v0
	v_mov_b32_e32 v50, v0
	v_mov_b32_e32 v51, v0
	v_mov_b32_e32 v52, v0
	v_mov_b32_e32 v53, v0
	v_mov_b32_e32 v54, v0
	v_mov_b32_e32 v55, v0
	v_mov_b32_e32 v8, v0
	v_mov_b32_e32 v9, v0
	v_mov_b32_e32 v10, v0
	v_mov_b32_e32 v11, v0
	v_mov_b32_e32 v12, v0
	v_mov_b32_e32 v13, v0
	v_mov_b32_e32 v14, v0
	v_mov_b32_e32 v15, v0
	v_mov_b32_e32 v24, v0
	v_mov_b32_e32 v25, v0
	v_mov_b32_e32 v26, v0
	v_mov_b32_e32 v27, v0
	v_mov_b32_e32 v28, v0
	v_mov_b32_e32 v29, v0
	v_mov_b32_e32 v30, v0
	v_mov_b32_e32 v31, v0
	v_mov_b32_e32 v40, v0
	v_mov_b32_e32 v41, v0
	v_mov_b32_e32 v42, v0
	v_mov_b32_e32 v43, v0
	v_mov_b32_e32 v44, v0
	v_mov_b32_e32 v45, v0
	v_mov_b32_e32 v46, v0
	v_mov_b32_e32 v47, v0
	v_mov_b32_e32 v64, v0
	v_mov_b32_e32 v65, v0
	v_mov_b32_e32 v66, v0
	v_mov_b32_e32 v67, v0
	v_mov_b32_e32 v68, v0
	v_mov_b32_e32 v69, v0
	v_mov_b32_e32 v70, v0
	v_mov_b32_e32 v71, v0
	v_mov_b32_e32 v80, v0
	v_mov_b32_e32 v81, v0
	v_mov_b32_e32 v82, v0
	v_mov_b32_e32 v83, v0
	s_waitcnt vmcnt(0)
	v_mov_b32_e32 v84, v0
	v_mov_b32_e32 v85, v0
	v_mov_b32_e32 v86, v0
	v_mov_b32_e32 v87, v0
	v_mov_b32_e32 v96, v0
	v_mov_b32_e32 v97, v0
	v_mov_b32_e32 v98, v0
	v_mov_b32_e32 v99, v0
	v_mov_b32_e32 v100, v0
	v_mov_b32_e32 v101, v0
	v_mov_b32_e32 v102, v0
	v_mov_b32_e32 v103, v0
	v_mov_b32_e32 v112, v0
	v_mov_b32_e32 v113, v0
	v_mov_b32_e32 v114, v0
	v_mov_b32_e32 v115, v0
	v_mov_b32_e32 v116, v0
	v_mov_b32_e32 v117, v0
	v_mov_b32_e32 v118, v0
	v_mov_b32_e32 v119, v0
	v_mov_b32_e32 v120, v0
	v_mov_b32_e32 v121, v0
	v_mov_b32_e32 v122, v0
	v_mov_b32_e32 v123, v0
	v_mov_b32_e32 v132, v0
	v_mov_b32_e32 v133, v0
	v_mov_b32_e32 v134, v0
	v_mov_b32_e32 v135, v0
	v_mov_b32_e32 v88, v0
	v_mov_b32_e32 v89, v0
	v_mov_b32_e32 v90, v0
	v_mov_b32_e32 v91, v0
	v_mov_b32_e32 v92, v0
	v_mov_b32_e32 v93, v0
	v_mov_b32_e32 v94, v0
	v_mov_b32_e32 v95, v0
	v_mov_b32_e32 v104, v0
	v_mov_b32_e32 v105, v0
	v_mov_b32_e32 v106, v0
	v_mov_b32_e32 v107, v0
	v_mov_b32_e32 v108, v0
	v_mov_b32_e32 v109, v0
	v_mov_b32_e32 v110, v0
	v_mov_b32_e32 v111, v0
	v_mov_b32_e32 v124, v0
	v_mov_b32_e32 v125, v0
	v_mov_b32_e32 v126, v0
	v_mov_b32_e32 v127, v0
	v_mov_b32_e32 v128, v0
	v_mov_b32_e32 v129, v0
	v_mov_b32_e32 v130, v0
	v_mov_b32_e32 v131, v0
	v_mov_b32_e32 v136, v0
	v_mov_b32_e32 v137, v0
	v_mov_b32_e32 v138, v0
	v_mov_b32_e32 v139, v0
	v_mov_b32_e32 v140, v0
	v_mov_b32_e32 v141, v0
	v_mov_b32_e32 v142, v0
	v_mov_b32_e32 v143, v0
	.p2align 6

; #define PG8_WAIT_V(n) asm volatile("s_waitcnt vmcnt(" #n ")" ::: "memory")
; #define PG8_WAIT_L(n) asm volatile("s_waitcnt lgkmcnt(" #n ")" ::: "memory")
; template <class Epi, class Sched, bool ALIGN_EPI>
; __device__ __forceinline__ void gemm_phase(LAS unsigned char* lds, const GemmDesc g, const Sched& S, const Epi& E) {
;     ...
;         const bool has_next = S.next(ui + 1, nxt);
;         const char* nA = has_next ? S.aptr(nxt) : cA; const char* nB = has_next ? S.bptr(nxt) : cB;
;         for (int t = 0; t < nt; t += 2) {
;             const bool last = (t == nt - 2);
;             const char* a1 = cA + (size_t)(t + 1) * kstep;
;             const char* a2 = last ? nA : cA + (size_t)(t + 2) * kstep; const char* b2 = last ? nB : cB + (size_t)(t + 2) * kstep;
;             const char* a3 = a2 + kstep; const char* b3 = b2 + kstep;
;             PG8_LDB(B0, 0, 0); PG8_LDB(B1, 0, 1); PG8_SCHED; PG8_LDA(At, 0, 0); PG8_STAGE(PG8_SA(1, 1), a1 + hstepA, voffA);
;             PG8_WAIT_V(8); PG8_WAIT_L(0); PG8_BAR; PG8_MMA(0, 0, At, B0); PG8_MMA(0, 1, At, B1); PG8_BAR; PG8_SCHED;
;             PG8_LDA(At, 0, 1); PG8_STAGE(PG8_SB(0, 0), b2, voffB); PG8_STAGE(PG8_SB(0, 1), b2 + hstepB, voffB); PG8_STAGE(PG8_SA(0, 0), a2, voffA);
;             PG8_WAIT_V(8); PG8_WAIT_L(0); PG8_BAR; PG8_MMA(1, 0, At, B0); PG8_MMA(1, 1, At, B1); PG8_BAR; PG8_SCHED;
;             PG8_LDB(B0, 1, 0); PG8_LDB(B1, 1, 1); PG8_SCHED; PG8_LDA(At, 1, 0); PG8_STAGE(PG8_SA(0, 1), a2 + hstepA, voffA);
;             PG8_WAIT_V(8); PG8_WAIT_L(0); PG8_BAR; PG8_MMA(0, 0, At, B0); PG8_MMA(0, 1, At, B1); PG8_BAR; PG8_SCHED;
;             PG8_LDA(At, 1, 1); PG8_STAGE(PG8_SB(1, 0), b3, voffB); PG8_STAGE(PG8_SB(1, 1), b3 + hstepB, voffB); PG8_STAGE(PG8_SA(1, 0), a3, voffA);
;             PG8_WAIT_V(8); PG8_WAIT_L(0); PG8_BAR; PG8_MMA(1, 0, At, B0); PG8_MMA(1, 1, At, B1); PG8_BAR; PG8_SCHED;
;         }
;         if constexpr (ALIGN_EPI) { if (wr == 0) PG8_BAR; }
;         E(acc, cur, wr, wc, fr, fq, lds + STAGE_BYTES);
;         if (!has_next) break;
; #pragma unroll
;         for (int a = 0; a < 2; ++a)
; #pragma unroll
;             for (int b = 0; b < 2; ++b)
; #pragma unroll
;                 for (int m = 0; m < 4; ++m)
; #pragma unroll
;                     for (int n = 0; n < 2; ++n) acc[a][b][m][n] = (f32x4){0.f, 0.f, 0.f, 0.f};
;         cur = nxt; cA = nA; cB = nB; ++ui;
.LBB0_820:
	s_ashr_i32 s27, s26, 31
	s_lshl_b64 s[30:31], s[26:27], 11
	s_add_u32 s30, s8, s30
	s_addc_u32 s31, s9, s31
	s_and_b64 s[34:35], s[6:7], exec
	s_cselect_b32 s1, s31, s37
	s_cselect_b32 s10, s30, s36
	s_ashr_i32 s29, s28, 31
	s_lshl_b64 s[34:35], s[28:29], 11
	v_readlane_b32 s12, v254, 57
	v_readlane_b32 s13, v254, 58
	s_add_u32 s34, s12, s34
	s_addc_u32 s35, s13, s35
	s_and_b64 s[40:41], s[6:7], exec
	s_cselect_b32 s21, s35, s39
	s_cselect_b32 s27, s34, s38
	s_add_u32 s36, s36, 0x40080
	s_addc_u32 s37, s37, 0
	s_add_u32 s29, s38, 0x100
	v_mov_b32_e32 v0, 0
	s_addc_u32 s71, s39, 0
	s_mov_b32 s72, -2
	v_mov_b32_e32 v1, v0
	s_waitcnt lgkmcnt(0)
	v_mov_b32_e32 v2, v0
	v_mov_b32_e32 v3, v0
	v_mov_b32_e32 v4, v0
	v_mov_b32_e32 v5, v0
	v_mov_b32_e32 v6, v0
	v_mov_b32_e32 v7, v0
	v_mov_b32_e32 v16, v0
	v_mov_b32_e32 v17, v0
	v_mov_b32_e32 v18, v0
	v_mov_b32_e32 v19, v0
	v_mov_b32_e32 v20, v0
	v_mov_b32_e32 v21, v0
	v_mov_b32_e32 v22, v0
	v_mov_b32_e32 v23, v0
	v_mov_b32_e32 v32, v0
	v_mov_b32_e32 v33, v0
	v_mov_b32_e32 v34, v0
	v_mov_b32_e32 v35, v0
	v_mov_b32_e32 v36, v0
	v_mov_b32_e32 v37, v0
	v_mov_b32_e32 v38, v0
	v_mov_b32_e32 v39, v0
	v_mov_b32_e32 v48, v0
	v_mov_b32_e32 v49, v0
	v_mov_b32_e32 v50, v0
	v_mov_b32_e32 v51, v0
	v_mov_b32_e32 v52, v0
	v_mov_b32_e32 v53, v0
	v_mov_b32_e32 v54, v0
	v_mov_b32_e32 v55, v0
	v_mov_b32_e32 v8, v0
	v_mov_b32_e32 v9, v0
	v_mov_b32_e32 v10, v0
	v_mov_b32_e32 v11, v0
	v_mov_b32_e32 v12, v0
	v_mov_b32_e32 v13, v0
	v_mov_b32_e32 v14, v0
	v_mov_b32_e32 v15, v0
	v_mov_b32_e32 v24, v0
	v_mov_b32_e32 v25, v0
	v_mov_b32_e32 v26, v0
	v_mov_b32_e32 v27, v0
	v_mov_b32_e32 v28, v0
	v_mov_b32_e32 v29, v0
	v_mov_b32_e32 v30, v0
	v_mov_b32_e32 v31, v0
	v_mov_b32_e32 v40, v0
	v_mov_b32_e32 v41, v0
	v_mov_b32_e32 v42, v0
	v_mov_b32_e32 v43, v0
	v_mov_b32_e32 v44, v0
	v_mov_b32_e32 v45, v0
	v_mov_b32_e32 v46, v0
	v_mov_b32_e32 v47, v0
	v_mov_b32_e32 v56, v0
	v_mov_b32_e32 v57, v0
	v_mov_b32_e32 v58, v0
	v_mov_b32_e32 v59, v0
	v_mov_b32_e32 v60, v0
	v_mov_b32_e32 v61, v0
	v_mov_b32_e32 v62, v0
	v_mov_b32_e32 v63, v0
	v_mov_b32_e32 v64, v0
	v_mov_b32_e32 v65, v0
	v_mov_b32_e32 v66, v0
	v_mov_b32_e32 v67, v0
	v_mov_b32_e32 v68, v0
	v_mov_b32_e32 v69, v0
	v_mov_b32_e32 v70, v0
	v_mov_b32_e32 v71, v0
	v_mov_b32_e32 v80, v0
	v_mov_b32_e32 v81, v0
	v_mov_b32_e32 v82, v0
	v_mov_b32_e32 v83, v0
	s_waitcnt vmcnt(0)
	v_mov_b32_e32 v84, v0
	v_mov_b32_e32 v85, v0
	v_mov_b32_e32 v86, v0
	v_mov_b32_e32 v87, v0
	v_mov_b32_e32 v96, v0
	v_mov_b32_e32 v97, v0
	v_mov_b32_e32 v98, v0
	v_mov_b32_e32 v99, v0
	v_mov_b32_e32 v100, v0
	v_mov_b32_e32 v101, v0
	v_mov_b32_e32 v102, v0
	v_mov_b32_e32 v103, v0
	v_mov_b32_e32 v112, v0
	v_mov_b32_e32 v113, v0
	v_mov_b32_e32 v114, v0
	v_mov_b32_e32 v115, v0
	v_mov_b32_e32 v116, v0
	v_mov_b32_e32 v117, v0
	v_mov_b32_e32 v118, v0
	v_mov_b32_e32 v119, v0
	v_mov_b32_e32 v72, v0
	v_mov_b32_e32 v73, v0
	v_mov_b32_e32 v74, v0
	v_mov_b32_e32 v75, v0
	v_mov_b32_e32 v76, v0
	v_mov_b32_e32 v77, v0
	v_mov_b32_e32 v78, v0
	v_mov_b32_e32 v79, v0
	v_mov_b32_e32 v88, v0
	v_mov_b32_e32 v89, v0
	v_mov_b32_e32 v90, v0
	v_mov_b32_e32 v91, v0
	v_mov_b32_e32 v92, v0
	v_mov_b32_e32 v93, v0
	v_mov_b32_e32 v94, v0
	v_mov_b32_e32 v95, v0
	v_mov_b32_e32 v104, v0
	v_mov_b32_e32 v105, v0
	v_mov_b32_e32 v106, v0
	v_mov_b32_e32 v107, v0
	v_mov_b32_e32 v108, v0
	v_mov_b32_e32 v109, v0
	v_mov_b32_e32 v110, v0
	v_mov_b32_e32 v111, v0
	v_mov_b32_e32 v120, v0
	v_mov_b32_e32 v121, v0
	v_mov_b32_e32 v122, v0
	v_mov_b32_e32 v123, v0
	v_mov_b32_e32 v124, v0
	v_mov_b32_e32 v125, v0
	v_mov_b32_e32 v126, v0
	v_mov_b32_e32 v127, v0
	.p2align 6

; #define PG8_WAIT_V(n) asm volatile("s_waitcnt vmcnt(" #n ")" ::: "memory")
; #define PG8_WAIT_L(n) asm volatile("s_waitcnt lgkmcnt(" #n ")" ::: "memory")
; template <class Epi, class Sched, bool ALIGN_EPI>
; __device__ __forceinline__ void gemm_phase(LAS unsigned char* lds, const GemmDesc g, const Sched& S, const Epi& E) {
;     ...
;         const bool has_next = S.next(ui + 1, nxt);
;         const char* nA = has_next ? S.aptr(nxt) : cA; const char* nB = has_next ? S.bptr(nxt) : cB;
;         for (int t = 0; t < nt; t += 2) {
;             const bool last = (t == nt - 2);
;             const char* a1 = cA + (size_t)(t + 1) * kstep;
;             const char* a2 = last ? nA : cA + (size_t)(t + 2) * kstep; const char* b2 = last ? nB : cB + (size_t)(t + 2) * kstep;
;             const char* a3 = a2 + kstep; const char* b3 = b2 + kstep;
;             PG8_LDB(B0, 0, 0); PG8_LDB(B1, 0, 1); PG8_SCHED; PG8_LDA(At, 0, 0); PG8_STAGE(PG8_SA(1, 1), a1 + hstepA, voffA);
;             PG8_WAIT_V(8); PG8_WAIT_L(0); PG8_BAR; PG8_MMA(0, 0, At, B0); PG8_MMA(0, 1, At, B1); PG8_BAR; PG8_SCHED;
;             PG8_LDA(At, 0, 1); PG8_STAGE(PG8_SB(0, 0), b2, voffB); PG8_STAGE(PG8_SB(0, 1), b2 + hstepB, voffB); PG8_STAGE(PG8_SA(0, 0), a2, voffA);
;             PG8_WAIT_V(8); PG8_WAIT_L(0); PG8_BAR; PG8_MMA(1, 0, At, B0); PG8_MMA(1, 1, At, B1); PG8_BAR; PG8_SCHED;
;             PG8_LDB(B0, 1, 0); PG8_LDB(B1, 1, 1); PG8_SCHED; PG8_LDA(At, 1, 0); PG8_STAGE(PG8_SA(0, 1), a2 + hstepA, voffA);
;             PG8_WAIT_V(8); PG8_WAIT_L(0); PG8_BAR; PG8_MMA(0, 0, At, B0); PG8_MMA(0, 1, At, B1); PG8_BAR; PG8_SCHED;
;             PG8_LDA(At, 1, 1); PG8_STAGE(PG8_SB(1, 0), b3, voffB); PG8_STAGE(PG8_SB(1, 1), b3 + hstepB, voffB); PG8_STAGE(PG8_SA(1, 0), a3, voffA);
;             PG8_WAIT_V(8); PG8_WAIT_L(0); PG8_BAR; PG8_MMA(1, 0, At, B0); PG8_MMA(1, 1, At, B1); PG8_BAR; PG8_SCHED;
;         }
;         if constexpr (ALIGN_EPI) { if (wr == 0) PG8_BAR; }
;         E(acc, cur, wr, wc, fr, fq, lds + STAGE_BYTES);
;         if (!has_next) break;
; #pragma unroll
;         for (int a = 0; a < 2; ++a)
; #pragma unroll
;             for (int b = 0; b < 2; ++b)
; #pragma unroll
;                 for (int m = 0; m < 4; ++m)
; #pragma unroll
;                     for (int n = 0; n < 2; ++n) acc[a][b][m][n] = (f32x4){0.f, 0.f, 0.f, 0.f};
;         cur = nxt; cA = nA; cB = nB; ++ui;
.LBB0_941:
	s_ashr_i32 s29, s28, 31
	s_lshl_b64 s[34:35], s[28:29], 11
	s_add_u32 s34, s60, s34
	s_addc_u32 s35, s61, s35
	s_and_b64 s[36:37], s[30:31], exec
	s_cselect_b32 s21, s35, s65
	s_cselect_b32 s29, s34, s64
	s_ashr_i32 s27, s26, 31
	s_lshl_b64 s[36:37], s[26:27], 11
	v_readlane_b32 s12, v254, 59
	v_readlane_b32 s13, v254, 60
	s_add_u32 s36, s12, s36
	s_addc_u32 s37, s13, s37
	s_and_b64 s[66:67], s[30:31], exec
	s_cselect_b32 s27, s37, s41
	s_cselect_b32 s79, s36, s40
	s_add_u32 s64, s64, 0x40080
	s_addc_u32 s65, s65, 0
	s_add_u32 s80, s40, 0x100
	v_mov_b32_e32 v0, 0
	s_addc_u32 s81, s41, 0
	s_mov_b32 s82, -2
	v_mov_b32_e32 v1, v0
	v_mov_b32_e32 v2, v0
	v_mov_b32_e32 v3, v0
	v_mov_b32_e32 v4, v0
	v_mov_b32_e32 v5, v0
	v_mov_b32_e32 v6, v0
	v_mov_b32_e32 v7, v0
	v_mov_b32_e32 v16, v0
	v_mov_b32_e32 v17, v0
	v_mov_b32_e32 v18, v0
	v_mov_b32_e32 v19, v0
	v_mov_b32_e32 v20, v0
	v_mov_b32_e32 v21, v0
	v_mov_b32_e32 v22, v0
	v_mov_b32_e32 v23, v0
	v_mov_b32_e32 v32, v0
	v_mov_b32_e32 v33, v0
	v_mov_b32_e32 v34, v0
	v_mov_b32_e32 v35, v0
	v_mov_b32_e32 v36, v0
	v_mov_b32_e32 v37, v0
	v_mov_b32_e32 v38, v0
	v_mov_b32_e32 v39, v0
	v_mov_b32_e32 v48, v0
	v_mov_b32_e32 v49, v0
	v_mov_b32_e32 v50, v0
	v_mov_b32_e32 v51, v0
	v_mov_b32_e32 v52, v0
	v_mov_b32_e32 v53, v0
	v_mov_b32_e32 v54, v0
	v_mov_b32_e32 v55, v0
	v_mov_b32_e32 v8, v0
	v_mov_b32_e32 v9, v0
	v_mov_b32_e32 v10, v0
	v_mov_b32_e32 v11, v0
	v_mov_b32_e32 v12, v0
	v_mov_b32_e32 v13, v0
	v_mov_b32_e32 v14, v0
	v_mov_b32_e32 v15, v0
	v_mov_b32_e32 v24, v0
	v_mov_b32_e32 v25, v0
	v_mov_b32_e32 v26, v0
	v_mov_b32_e32 v27, v0
	v_mov_b32_e32 v28, v0
	v_mov_b32_e32 v29, v0
	v_mov_b32_e32 v30, v0
	v_mov_b32_e32 v31, v0
	v_mov_b32_e32 v40, v0
	v_mov_b32_e32 v41, v0
	v_mov_b32_e32 v42, v0
	v_mov_b32_e32 v43, v0
	v_mov_b32_e32 v44, v0
	v_mov_b32_e32 v45, v0
	v_mov_b32_e32 v46, v0
	v_mov_b32_e32 v47, v0
	v_mov_b32_e32 v56, v0
	v_mov_b32_e32 v57, v0
	v_mov_b32_e32 v58, v0
	v_mov_b32_e32 v59, v0
	v_mov_b32_e32 v60, v0
	v_mov_b32_e32 v61, v0
	v_mov_b32_e32 v62, v0
	v_mov_b32_e32 v63, v0
	v_mov_b32_e32 v64, v0
	v_mov_b32_e32 v65, v0
	v_mov_b32_e32 v66, v0
	v_mov_b32_e32 v67, v0
	v_mov_b32_e32 v68, v0
	v_mov_b32_e32 v69, v0
	v_mov_b32_e32 v70, v0
	v_mov_b32_e32 v71, v0
	v_mov_b32_e32 v80, v0
	v_mov_b32_e32 v81, v0
	v_mov_b32_e32 v82, v0
	v_mov_b32_e32 v83, v0
	s_waitcnt vmcnt(0)
	v_mov_b32_e32 v84, v0
	v_mov_b32_e32 v85, v0
	v_mov_b32_e32 v86, v0
	v_mov_b32_e32 v87, v0
	v_mov_b32_e32 v96, v0
	v_mov_b32_e32 v97, v0
	v_mov_b32_e32 v98, v0
	v_mov_b32_e32 v99, v0
	v_mov_b32_e32 v100, v0
	v_mov_b32_e32 v101, v0
	v_mov_b32_e32 v102, v0
	v_mov_b32_e32 v103, v0
	v_mov_b32_e32 v104, v0
	v_mov_b32_e32 v105, v0
	v_mov_b32_e32 v106, v0
	v_mov_b32_e32 v107, v0
	v_mov_b32_e32 v108, v0
	v_mov_b32_e32 v109, v0
	v_mov_b32_e32 v110, v0
	v_mov_b32_e32 v111, v0
	v_mov_b32_e32 v72, v0
	v_mov_b32_e32 v73, v0
	v_mov_b32_e32 v74, v0
	v_mov_b32_e32 v75, v0
	v_mov_b32_e32 v76, v0
	v_mov_b32_e32 v77, v0
	v_mov_b32_e32 v78, v0
	v_mov_b32_e32 v79, v0
	v_mov_b32_e32 v88, v0
	v_mov_b32_e32 v89, v0
	v_mov_b32_e32 v90, v0
	v_mov_b32_e32 v91, v0
	v_mov_b32_e32 v92, v0
	v_mov_b32_e32 v93, v0
	v_mov_b32_e32 v94, v0
	v_mov_b32_e32 v95, v0
	v_mov_b32_e32 v112, v0
	v_mov_b32_e32 v113, v0
	v_mov_b32_e32 v114, v0
	v_mov_b32_e32 v115, v0
	v_mov_b32_e32 v116, v0
	v_mov_b32_e32 v117, v0
	v_mov_b32_e32 v118, v0
	v_mov_b32_e32 v119, v0
	v_mov_b32_e32 v120, v0
	v_mov_b32_e32 v121, v0
	v_mov_b32_e32 v122, v0
	v_mov_b32_e32 v123, v0
	v_mov_b32_e32 v124, v0
	v_mov_b32_e32 v125, v0
	v_mov_b32_e32 v126, v0
	v_mov_b32_e32 v127, v0
	.p2align 6

; #define PG8_WAIT_V(n) asm volatile("s_waitcnt vmcnt(" #n ")" ::: "memory")
; #define PG8_WAIT_L(n) asm volatile("s_waitcnt lgkmcnt(" #n ")" ::: "memory")
; template <class Epi, class Sched, bool ALIGN_EPI>
; __device__ __forceinline__ void gemm_phase(LAS unsigned char* lds, const GemmDesc g, const Sched& S, const Epi& E) {
;     ...
;         const bool has_next = S.next(ui + 1, nxt);
;         const char* nA = has_next ? S.aptr(nxt) : cA; const char* nB = has_next ? S.bptr(nxt) : cB;
;         for (int t = 0; t < nt; t += 2) {
;             const bool last = (t == nt - 2);
;             const char* a1 = cA + (size_t)(t + 1) * kstep;
;             const char* a2 = last ? nA : cA + (size_t)(t + 2) * kstep; const char* b2 = last ? nB : cB + (size_t)(t + 2) * kstep;
;             const char* a3 = a2 + kstep; const char* b3 = b2 + kstep;
;             PG8_LDB(B0, 0, 0); PG8_LDB(B1, 0, 1); PG8_SCHED; PG8_LDA(At, 0, 0); PG8_STAGE(PG8_SA(1, 1), a1 + hstepA, voffA);
;             PG8_WAIT_V(8); PG8_WAIT_L(0); PG8_BAR; PG8_MMA(0, 0, At, B0); PG8_MMA(0, 1, At, B1); PG8_BAR; PG8_SCHED;
;             PG8_LDA(At, 0, 1); PG8_STAGE(PG8_SB(0, 0), b2, voffB); PG8_STAGE(PG8_SB(0, 1), b2 + hstepB, voffB); PG8_STAGE(PG8_SA(0, 0), a2, voffA);
;             PG8_WAIT_V(8); PG8_WAIT_L(0); PG8_BAR; PG8_MMA(1, 0, At, B0); PG8_MMA(1, 1, At, B1); PG8_BAR; PG8_SCHED;
;             PG8_LDB(B0, 1, 0); PG8_LDB(B1, 1, 1); PG8_SCHED; PG8_LDA(At, 1, 0); PG8_STAGE(PG8_SA(0, 1), a2 + hstepA, voffA);
;             PG8_WAIT_V(8); PG8_WAIT_L(0); PG8_BAR; PG8_MMA(0, 0, At, B0); PG8_MMA(0, 1, At, B1); PG8_BAR; PG8_SCHED;
;             PG8_LDA(At, 1, 1); PG8_STAGE(PG8_SB(1, 0), b3, voffB); PG8_STAGE(PG8_SB(1, 1), b3 + hstepB, voffB); PG8_STAGE(PG8_SA(1, 0), a3, voffA);
;             PG8_WAIT_V(8); PG8_WAIT_L(0); PG8_BAR; PG8_MMA(1, 0, At, B0); PG8_MMA(1, 1, At, B1); PG8_BAR; PG8_SCHED;
;         }
;         if constexpr (ALIGN_EPI) { if (wr == 0) PG8_BAR; }
;         E(acc, cur, wr, wc, fr, fq, lds + STAGE_BYTES);
;         if (!has_next) break;
; #pragma unroll
;         for (int a = 0; a < 2; ++a)
; #pragma unroll
;             for (int b = 0; b < 2; ++b)
; #pragma unroll
;                 for (int m = 0; m < 4; ++m)
; #pragma unroll
;                     for (int n = 0; n < 2; ++n) acc[a][b][m][n] = (f32x4){0.f, 0.f, 0.f, 0.f};
;         cur = nxt; cA = nA; cB = nB; ++ui;
.LBB0_1256:
	s_ashr_i32 s39, s38, 31
	s_lshl_b64 s[4:5], s[38:39], 11
	s_mov_b64 s[6:7], s[74:75]
	s_add_u32 s62, s6, s4
	s_addc_u32 s63, s7, s5
	s_and_b64 s[4:5], s[10:11], exec
	s_cselect_b32 s1, s63, s65
	s_cselect_b32 s4, s62, s64
	s_add_u32 s10, s64, 0x40080
	s_addc_u32 s11, s65, 0
	s_add_u32 s5, s40, 0x100
	v_mov_b32_e32 v0, 0
	s_addc_u32 s6, s41, 0
	s_mov_b32 s7, -2
	v_mov_b32_e32 v1, v0
	s_waitcnt lgkmcnt(0)
	v_mov_b32_e32 v2, v0
	v_mov_b32_e32 v3, v0
	v_mov_b32_e32 v4, v0
	v_mov_b32_e32 v5, v0
	v_mov_b32_e32 v6, v0
	v_mov_b32_e32 v7, v0
	v_mov_b32_e32 v16, v0
	v_mov_b32_e32 v17, v0
	v_mov_b32_e32 v18, v0
	v_mov_b32_e32 v19, v0
	v_mov_b32_e32 v20, v0
	v_mov_b32_e32 v21, v0
	v_mov_b32_e32 v22, v0
	v_mov_b32_e32 v23, v0
	v_mov_b32_e32 v32, v0
	v_mov_b32_e32 v33, v0
	v_mov_b32_e32 v34, v0
	v_mov_b32_e32 v35, v0
	v_mov_b32_e32 v36, v0
	v_mov_b32_e32 v37, v0
	v_mov_b32_e32 v38, v0
	v_mov_b32_e32 v39, v0
	v_mov_b32_e32 v48, v0
	v_mov_b32_e32 v49, v0
	v_mov_b32_e32 v50, v0
	v_mov_b32_e32 v51, v0
	v_mov_b32_e32 v52, v0
	v_mov_b32_e32 v53, v0
	v_mov_b32_e32 v54, v0
	v_mov_b32_e32 v55, v0
	v_mov_b32_e32 v8, v0
	v_mov_b32_e32 v9, v0
	v_mov_b32_e32 v10, v0
	v_mov_b32_e32 v11, v0
	v_mov_b32_e32 v12, v0
	v_mov_b32_e32 v13, v0
	v_mov_b32_e32 v14, v0
	v_mov_b32_e32 v15, v0
	v_mov_b32_e32 v24, v0
	v_mov_b32_e32 v25, v0
	v_mov_b32_e32 v26, v0
	v_mov_b32_e32 v27, v0
	v_mov_b32_e32 v28, v0
	v_mov_b32_e32 v29, v0
	v_mov_b32_e32 v30, v0
	v_mov_b32_e32 v31, v0
	v_mov_b32_e32 v40, v0
	v_mov_b32_e32 v41, v0
	v_mov_b32_e32 v42, v0
	v_mov_b32_e32 v43, v0
	v_mov_b32_e32 v44, v0
	v_mov_b32_e32 v45, v0
	v_mov_b32_e32 v46, v0
	v_mov_b32_e32 v47, v0
	v_mov_b32_e32 v56, v0
	v_mov_b32_e32 v57, v0
	v_mov_b32_e32 v58, v0
	v_mov_b32_e32 v59, v0
	v_mov_b32_e32 v60, v0
	v_mov_b32_e32 v61, v0
	v_mov_b32_e32 v62, v0
	v_mov_b32_e32 v63, v0
	v_mov_b32_e32 v96, v0
	v_mov_b32_e32 v97, v0
	v_mov_b32_e32 v98, v0
	v_mov_b32_e32 v99, v0
	v_mov_b32_e32 v100, v0
	v_mov_b32_e32 v101, v0
	v_mov_b32_e32 v102, v0
	v_mov_b32_e32 v103, v0
	v_mov_b32_e32 v112, v0
	v_mov_b32_e32 v113, v0
	v_mov_b32_e32 v114, v0
	v_mov_b32_e32 v115, v0
	v_mov_b32_e32 v116, v0
	v_mov_b32_e32 v117, v0
	v_mov_b32_e32 v118, v0
	v_mov_b32_e32 v119, v0
	v_mov_b32_e32 v128, v0
	v_mov_b32_e32 v129, v0
	v_mov_b32_e32 v130, v0
	v_mov_b32_e32 v131, v0
	v_mov_b32_e32 v132, v0
	v_mov_b32_e32 v133, v0
	v_mov_b32_e32 v134, v0
	v_mov_b32_e32 v135, v0
	v_mov_b32_e32 v144, v0
	v_mov_b32_e32 v145, v0
	v_mov_b32_e32 v146, v0
	v_mov_b32_e32 v147, v0
	v_mov_b32_e32 v148, v0
	v_mov_b32_e32 v149, v0
	v_mov_b32_e32 v150, v0
	v_mov_b32_e32 v151, v0
	v_mov_b32_e32 v104, v0
	v_mov_b32_e32 v105, v0
	v_mov_b32_e32 v106, v0
	v_mov_b32_e32 v107, v0
	v_mov_b32_e32 v108, v0
	v_mov_b32_e32 v109, v0
	v_mov_b32_e32 v110, v0
	v_mov_b32_e32 v111, v0
	v_mov_b32_e32 v120, v0
	v_mov_b32_e32 v121, v0
	v_mov_b32_e32 v122, v0
	v_mov_b32_e32 v123, v0
	v_mov_b32_e32 v124, v0
	v_mov_b32_e32 v125, v0
	v_mov_b32_e32 v126, v0
	v_mov_b32_e32 v127, v0
	v_mov_b32_e32 v136, v0
	v_mov_b32_e32 v137, v0
	v_mov_b32_e32 v138, v0
	v_mov_b32_e32 v139, v0
	v_mov_b32_e32 v140, v0
	v_mov_b32_e32 v141, v0
	v_mov_b32_e32 v142, v0
	v_mov_b32_e32 v143, v0
	v_mov_b32_e32 v152, v0
	v_mov_b32_e32 v153, v0
	v_mov_b32_e32 v154, v0
	v_mov_b32_e32 v155, v0
	v_mov_b32_e32 v156, v0
	v_mov_b32_e32 v157, v0
	v_mov_b32_e32 v158, v0
	v_mov_b32_e32 v159, v0
	.p2align 6

; #define PG8_WAIT_V(n) asm volatile("s_waitcnt vmcnt(" #n ")" ::: "memory")
; #define PG8_WAIT_L(n) asm volatile("s_waitcnt lgkmcnt(" #n ")" ::: "memory")
; template <class Epi, class Sched, bool ALIGN_EPI>
; __device__ __forceinline__ void gemm_phase(LAS unsigned char* lds, const GemmDesc g, const Sched& S, const Epi& E) {
;     ...
;         const bool has_next = S.next(ui + 1, nxt);
;         const char* nA = has_next ? S.aptr(nxt) : cA; const char* nB = has_next ? S.bptr(nxt) : cB;
;         for (int t = 0; t < nt; t += 2) {
;             const bool last = (t == nt - 2);
;             const char* a1 = cA + (size_t)(t + 1) * kstep;
;             const char* a2 = last ? nA : cA + (size_t)(t + 2) * kstep; const char* b2 = last ? nB : cB + (size_t)(t + 2) * kstep;
;             const char* a3 = a2 + kstep; const char* b3 = b2 + kstep;
;             PG8_LDB(B0, 0, 0); PG8_LDB(B1, 0, 1); PG8_SCHED; PG8_LDA(At, 0, 0); PG8_STAGE(PG8_SA(1, 1), a1 + hstepA, voffA);
;             PG8_WAIT_V(8); PG8_WAIT_L(0); PG8_BAR; PG8_MMA(0, 0, At, B0); PG8_MMA(0, 1, At, B1); PG8_BAR; PG8_SCHED;
;             PG8_LDA(At, 0, 1); PG8_STAGE(PG8_SB(0, 0), b2, voffB); PG8_STAGE(PG8_SB(0, 1), b2 + hstepB, voffB); PG8_STAGE(PG8_SA(0, 0), a2, voffA);
;             PG8_WAIT_V(8); PG8_WAIT_L(0); PG8_BAR; PG8_MMA(1, 0, At, B0); PG8_MMA(1, 1, At, B1); PG8_BAR; PG8_SCHED;
;             PG8_LDB(B0, 1, 0); PG8_LDB(B1, 1, 1); PG8_SCHED; PG8_LDA(At, 1, 0); PG8_STAGE(PG8_SA(0, 1), a2 + hstepA, voffA);
;             PG8_WAIT_V(8); PG8_WAIT_L(0); PG8_BAR; PG8_MMA(0, 0, At, B0); PG8_MMA(0, 1, At, B1); PG8_BAR; PG8_SCHED;
;             PG8_LDA(At, 1, 1); PG8_STAGE(PG8_SB(1, 0), b3, voffB); PG8_STAGE(PG8_SB(1, 1), b3 + hstepB, voffB); PG8_STAGE(PG8_SA(1, 0), a3, voffA);
;             PG8_WAIT_V(8); PG8_WAIT_L(0); PG8_BAR; PG8_MMA(1, 0, At, B0); PG8_MMA(1, 1, At, B1); PG8_BAR; PG8_SCHED;
;         }
;         if constexpr (ALIGN_EPI) { if (wr == 0) PG8_BAR; }
;         E(acc, cur, wr, wc, fr, fq, lds + STAGE_BYTES);
;         if (!has_next) break;
; #pragma unroll
;         for (int a = 0; a < 2; ++a)
; #pragma unroll
;             for (int b = 0; b < 2; ++b)
; #pragma unroll
;                 for (int m = 0; m < 4; ++m)
; #pragma unroll
;                     for (int n = 0; n < 2; ++n) acc[a][b][m][n] = (f32x4){0.f, 0.f, 0.f, 0.f};
;         cur = nxt; cA = nA; cB = nB; ++ui;
.LBB0_1377:
	s_ashr_i32 s27, s26, 31
	s_lshl_b64 s[30:31], s[26:27], 11
	s_add_u32 s30, s88, s30
	s_addc_u32 s31, s89, s31
	s_and_b64 s[34:35], s[28:29], exec
	s_cselect_b32 s21, s31, s39
	s_cselect_b32 s27, s30, s38
	s_ashr_i32 s25, s24, 31
	s_lshl_b64 s[34:35], s[24:25], 11
	s_add_u32 s34, s4, s34
	s_addc_u32 s35, s5, s35
	s_and_b64 s[46:47], s[28:29], exec
	s_cselect_b32 s25, s35, s41
	s_cselect_b32 s67, s34, s40
	s_add_u32 s38, s38, 0x40080
	s_addc_u32 s39, s39, 0
	s_add_u32 s68, s40, 0x100
	v_mov_b32_e32 v0, 0
	s_addc_u32 s69, s41, 0
	s_mov_b32 s70, -2
	v_mov_b32_e32 v1, v0
	v_mov_b32_e32 v2, v0
	v_mov_b32_e32 v3, v0
	v_mov_b32_e32 v4, v0
	v_mov_b32_e32 v5, v0
	v_mov_b32_e32 v6, v0
	v_mov_b32_e32 v7, v0
	v_mov_b32_e32 v16, v0
	v_mov_b32_e32 v17, v0
	v_mov_b32_e32 v18, v0
	v_mov_b32_e32 v19, v0
	v_mov_b32_e32 v20, v0
	v_mov_b32_e32 v21, v0
	v_mov_b32_e32 v22, v0
	v_mov_b32_e32 v23, v0
	v_mov_b32_e32 v32, v0
	v_mov_b32_e32 v33, v0
	v_mov_b32_e32 v34, v0
	v_mov_b32_e32 v35, v0
	v_mov_b32_e32 v36, v0
	v_mov_b32_e32 v37, v0
	v_mov_b32_e32 v38, v0
	v_mov_b32_e32 v39, v0
	v_mov_b32_e32 v48, v0
	v_mov_b32_e32 v49, v0
	v_mov_b32_e32 v50, v0
	v_mov_b32_e32 v51, v0
	v_mov_b32_e32 v52, v0
	v_mov_b32_e32 v53, v0
	v_mov_b32_e32 v54, v0
	v_mov_b32_e32 v55, v0
	v_mov_b32_e32 v8, v0
	v_mov_b32_e32 v9, v0
	v_mov_b32_e32 v10, v0
	v_mov_b32_e32 v11, v0
	v_mov_b32_e32 v12, v0
	v_mov_b32_e32 v13, v0
	v_mov_b32_e32 v14, v0
	v_mov_b32_e32 v15, v0
	v_mov_b32_e32 v24, v0
	v_mov_b32_e32 v25, v0
	v_mov_b32_e32 v26, v0
	v_mov_b32_e32 v27, v0
	v_mov_b32_e32 v28, v0
	v_mov_b32_e32 v29, v0
	v_mov_b32_e32 v30, v0
	v_mov_b32_e32 v31, v0
	v_mov_b32_e32 v40, v0
	v_mov_b32_e32 v41, v0
	v_mov_b32_e32 v42, v0
	v_mov_b32_e32 v43, v0
	v_mov_b32_e32 v44, v0
	v_mov_b32_e32 v45, v0
	v_mov_b32_e32 v46, v0
	v_mov_b32_e32 v47, v0
	v_mov_b32_e32 v56, v0
	v_mov_b32_e32 v57, v0
	v_mov_b32_e32 v58, v0
	v_mov_b32_e32 v59, v0
	v_mov_b32_e32 v60, v0
	v_mov_b32_e32 v61, v0
	v_mov_b32_e32 v62, v0
	v_mov_b32_e32 v63, v0
	v_mov_b32_e32 v64, v0
	v_mov_b32_e32 v65, v0
	v_mov_b32_e32 v66, v0
	v_mov_b32_e32 v67, v0
	v_mov_b32_e32 v68, v0
	v_mov_b32_e32 v69, v0
	v_mov_b32_e32 v70, v0
	v_mov_b32_e32 v71, v0
	v_mov_b32_e32 v80, v0
	v_mov_b32_e32 v81, v0
	v_mov_b32_e32 v82, v0
	v_mov_b32_e32 v83, v0
	v_mov_b32_e32 v84, v0
	v_mov_b32_e32 v85, v0
	v_mov_b32_e32 v86, v0
	v_mov_b32_e32 v87, v0
	v_mov_b32_e32 v96, v0
	v_mov_b32_e32 v97, v0
	v_mov_b32_e32 v98, v0
	v_mov_b32_e32 v99, v0
	v_mov_b32_e32 v100, v0
	v_mov_b32_e32 v101, v0
	v_mov_b32_e32 v102, v0
	v_mov_b32_e32 v103, v0
	v_mov_b32_e32 v112, v0
	v_mov_b32_e32 v113, v0
	v_mov_b32_e32 v114, v0
	v_mov_b32_e32 v115, v0
	v_mov_b32_e32 v116, v0
	v_mov_b32_e32 v117, v0
	v_mov_b32_e32 v118, v0
	v_mov_b32_e32 v119, v0
	v_mov_b32_e32 v72, v0
	v_mov_b32_e32 v73, v0
	v_mov_b32_e32 v74, v0
	v_mov_b32_e32 v75, v0
	v_mov_b32_e32 v76, v0
	v_mov_b32_e32 v77, v0
	v_mov_b32_e32 v78, v0
	v_mov_b32_e32 v79, v0
	v_mov_b32_e32 v88, v0
	v_mov_b32_e32 v89, v0
	v_mov_b32_e32 v90, v0
	v_mov_b32_e32 v91, v0
	v_mov_b32_e32 v92, v0
	v_mov_b32_e32 v93, v0
	v_mov_b32_e32 v94, v0
	v_mov_b32_e32 v95, v0
	v_mov_b32_e32 v104, v0
	v_mov_b32_e32 v105, v0
	v_mov_b32_e32 v106, v0
	v_mov_b32_e32 v107, v0
	v_mov_b32_e32 v108, v0
	v_mov_b32_e32 v109, v0
	v_mov_b32_e32 v110, v0
	v_mov_b32_e32 v111, v0
	v_mov_b32_e32 v120, v0
	v_mov_b32_e32 v121, v0
	v_mov_b32_e32 v122, v0
	v_mov_b32_e32 v123, v0
	v_mov_b32_e32 v124, v0
	v_mov_b32_e32 v125, v0
	v_mov_b32_e32 v126, v0
	v_mov_b32_e32 v127, v0
	.p2align 6

; #define PG8_WAIT_V(n) asm volatile("s_waitcnt vmcnt(" #n ")" ::: "memory")
; #define PG8_WAIT_L(n) asm volatile("s_waitcnt lgkmcnt(" #n ")" ::: "memory")
; template <class Epi, class Sched, bool ALIGN_EPI>
; __device__ __forceinline__ void gemm_phase(LAS unsigned char* lds, const GemmDesc g, const Sched& S, const Epi& E) {
;     ...
;         const bool has_next = S.next(ui + 1, nxt);
;         const char* nA = has_next ? S.aptr(nxt) : cA; const char* nB = has_next ? S.bptr(nxt) : cB;
;         for (int t = 0; t < nt; t += 2) {
;             const bool last = (t == nt - 2);
;             const char* a1 = cA + (size_t)(t + 1) * kstep;
;             const char* a2 = last ? nA : cA + (size_t)(t + 2) * kstep; const char* b2 = last ? nB : cB + (size_t)(t + 2) * kstep;
;             const char* a3 = a2 + kstep; const char* b3 = b2 + kstep;
;             PG8_LDB(B0, 0, 0); PG8_LDB(B1, 0, 1); PG8_SCHED; PG8_LDA(At, 0, 0); PG8_STAGE(PG8_SA(1, 1), a1 + hstepA, voffA);
;             PG8_WAIT_V(8); PG8_WAIT_L(0); PG8_BAR; PG8_MMA(0, 0, At, B0); PG8_MMA(0, 1, At, B1); PG8_BAR; PG8_SCHED;
;             PG8_LDA(At, 0, 1); PG8_STAGE(PG8_SB(0, 0), b2, voffB); PG8_STAGE(PG8_SB(0, 1), b2 + hstepB, voffB); PG8_STAGE(PG8_SA(0, 0), a2, voffA);
;             PG8_WAIT_V(8); PG8_WAIT_L(0); PG8_BAR; PG8_MMA(1, 0, At, B0); PG8_MMA(1, 1, At, B1); PG8_BAR; PG8_SCHED;
;             PG8_LDB(B0, 1, 0); PG8_LDB(B1, 1, 1); PG8_SCHED; PG8_LDA(At, 1, 0); PG8_STAGE(PG8_SA(0, 1), a2 + hstepA, voffA);
;             PG8_WAIT_V(8); PG8_WAIT_L(0); PG8_BAR; PG8_MMA(0, 0, At, B0); PG8_MMA(0, 1, At, B1); PG8_BAR; PG8_SCHED;
;             PG8_LDA(At, 1, 1); PG8_STAGE(PG8_SB(1, 0), b3, voffB); PG8_STAGE(PG8_SB(1, 1), b3 + hstepB, voffB); PG8_STAGE(PG8_SA(1, 0), a3, voffA);
;             PG8_WAIT_V(8); PG8_WAIT_L(0); PG8_BAR; PG8_MMA(1, 0, At, B0); PG8_MMA(1, 1, At, B1); PG8_BAR; PG8_SCHED;
;         }
;         if constexpr (ALIGN_EPI) { if (wr == 0) PG8_BAR; }
;         E(acc, cur, wr, wc, fr, fq, lds + STAGE_BYTES);
;         if (!has_next) break;
; #pragma unroll
;         for (int a = 0; a < 2; ++a)
; #pragma unroll
;             for (int b = 0; b < 2; ++b)
; #pragma unroll
;                 for (int m = 0; m < 4; ++m)
; #pragma unroll
;                     for (int n = 0; n < 2; ++n) acc[a][b][m][n] = (f32x4){0.f, 0.f, 0.f, 0.f};
;         cur = nxt; cA = nA; cB = nB; ++ui;
.LBB0_1476:
	s_ashr_i32 s23, s22, 31
	s_lshl_b64 s[26:27], s[22:23], 13
	s_add_u32 s26, s44, s26
	s_addc_u32 s27, s45, s27
	s_and_b64 s[28:29], s[0:1], exec
	s_cselect_b32 s21, s27, s35
	s_cselect_b32 s23, s26, s34
	s_ashr_i32 s25, s24, 31
	s_lshl_b64 s[28:29], s[24:25], 13
	s_add_u32 s28, s6, s28
	s_addc_u32 s29, s7, s29
	s_and_b64 s[38:39], s[0:1], exec
	s_cselect_b32 s25, s29, s37
	s_cselect_b32 s62, s28, s36
	s_add_u32 s34, s34, 0x100080
	s_addc_u32 s35, s35, 0
	s_add_u32 s63, s36, 0x100
	v_mov_b32_e32 v0, 0
	s_addc_u32 s64, s37, 0
	s_mov_b32 s65, -2
	v_mov_b32_e32 v1, v0
	v_mov_b32_e32 v2, v0
	v_mov_b32_e32 v3, v0
	v_mov_b32_e32 v4, v0
	v_mov_b32_e32 v5, v0
	v_mov_b32_e32 v6, v0
	v_mov_b32_e32 v7, v0
	v_mov_b32_e32 v16, v0
	v_mov_b32_e32 v17, v0
	v_mov_b32_e32 v18, v0
	v_mov_b32_e32 v19, v0
	v_mov_b32_e32 v20, v0
	v_mov_b32_e32 v21, v0
	v_mov_b32_e32 v22, v0
	v_mov_b32_e32 v23, v0
	v_mov_b32_e32 v32, v0
	v_mov_b32_e32 v33, v0
	v_mov_b32_e32 v34, v0
	v_mov_b32_e32 v35, v0
	v_mov_b32_e32 v36, v0
	v_mov_b32_e32 v37, v0
	v_mov_b32_e32 v38, v0
	v_mov_b32_e32 v39, v0
	v_mov_b32_e32 v48, v0
	v_mov_b32_e32 v49, v0
	v_mov_b32_e32 v50, v0
	v_mov_b32_e32 v51, v0
	v_mov_b32_e32 v52, v0
	v_mov_b32_e32 v53, v0
	v_mov_b32_e32 v54, v0
	v_mov_b32_e32 v55, v0
	v_mov_b32_e32 v8, v0
	v_mov_b32_e32 v9, v0
	v_mov_b32_e32 v10, v0
	v_mov_b32_e32 v11, v0
	v_mov_b32_e32 v12, v0
	v_mov_b32_e32 v13, v0
	v_mov_b32_e32 v14, v0
	v_mov_b32_e32 v15, v0
	v_mov_b32_e32 v24, v0
	v_mov_b32_e32 v25, v0
	v_mov_b32_e32 v26, v0
	v_mov_b32_e32 v27, v0
	v_mov_b32_e32 v28, v0
	v_mov_b32_e32 v29, v0
	v_mov_b32_e32 v30, v0
	v_mov_b32_e32 v31, v0
	v_mov_b32_e32 v40, v0
	v_mov_b32_e32 v41, v0
	v_mov_b32_e32 v42, v0
	v_mov_b32_e32 v43, v0
	v_mov_b32_e32 v44, v0
	v_mov_b32_e32 v45, v0
	v_mov_b32_e32 v46, v0
	v_mov_b32_e32 v47, v0
	v_mov_b32_e32 v56, v0
	v_mov_b32_e32 v57, v0
	v_mov_b32_e32 v58, v0
	v_mov_b32_e32 v59, v0
	v_mov_b32_e32 v60, v0
	v_mov_b32_e32 v61, v0
	v_mov_b32_e32 v62, v0
	v_mov_b32_e32 v63, v0
	v_mov_b32_e32 v64, v0
	v_mov_b32_e32 v65, v0
	v_mov_b32_e32 v66, v0
	v_mov_b32_e32 v67, v0
	v_mov_b32_e32 v68, v0
	v_mov_b32_e32 v69, v0
	v_mov_b32_e32 v70, v0
	v_mov_b32_e32 v71, v0
	v_mov_b32_e32 v128, v0
	v_mov_b32_e32 v129, v0
	v_mov_b32_e32 v130, v0
	v_mov_b32_e32 v131, v0
	v_mov_b32_e32 v132, v0
	v_mov_b32_e32 v133, v0
	v_mov_b32_e32 v134, v0
	v_mov_b32_e32 v135, v0
	v_mov_b32_e32 v144, v0
	v_mov_b32_e32 v145, v0
	v_mov_b32_e32 v146, v0
	v_mov_b32_e32 v147, v0
	v_mov_b32_e32 v148, v0
	v_mov_b32_e32 v149, v0
	v_mov_b32_e32 v150, v0
	v_mov_b32_e32 v151, v0
	v_mov_b32_e32 v160, v0
	v_mov_b32_e32 v161, v0
	v_mov_b32_e32 v162, v0
	v_mov_b32_e32 v163, v0
	v_mov_b32_e32 v164, v0
	v_mov_b32_e32 v165, v0
	v_mov_b32_e32 v166, v0
	v_mov_b32_e32 v167, v0
	v_mov_b32_e32 v72, v0
	v_mov_b32_e32 v73, v0
	v_mov_b32_e32 v74, v0
	v_mov_b32_e32 v75, v0
	v_mov_b32_e32 v76, v0
	v_mov_b32_e32 v77, v0
	v_mov_b32_e32 v78, v0
	v_mov_b32_e32 v79, v0
	v_mov_b32_e32 v136, v0
	v_mov_b32_e32 v137, v0
	v_mov_b32_e32 v138, v0
	v_mov_b32_e32 v139, v0
	v_mov_b32_e32 v140, v0
	v_mov_b32_e32 v141, v0
	v_mov_b32_e32 v142, v0
	v_mov_b32_e32 v143, v0
	v_mov_b32_e32 v152, v0
	v_mov_b32_e32 v153, v0
	v_mov_b32_e32 v154, v0
	v_mov_b32_e32 v155, v0
	v_mov_b32_e32 v156, v0
	v_mov_b32_e32 v157, v0
	v_mov_b32_e32 v158, v0
	v_mov_b32_e32 v159, v0
	v_mov_b32_e32 v168, v0
	v_mov_b32_e32 v169, v0
	v_mov_b32_e32 v170, v0
	v_mov_b32_e32 v171, v0
	v_mov_b32_e32 v172, v0
	v_mov_b32_e32 v173, v0
	v_mov_b32_e32 v174, v0
	v_mov_b32_e32 v175, v0
	.p2align 6
